# residual-stream copy folded into the layer-0 rmsnorm pass (reads the inputs directly, writes the working copy); separate copy phase removed
# speedup vs baseline: 1.0073x; 1.0018x over previous
.Lnm1_end:
.Lnm1_done:
.LBB0_91:
	s_or_b64 exec, exec, s[4:5]

.LBB0_254:
	s_andn2_b64 vcc, exec, s[4:5]
	s_cbranch_vccnz .LBB0_262
	v_readlane_b32 s0, v254, 48
	s_cmp_lg_u32 s0, 1
	s_cbranch_scc1 .LBB0_262
	v_mov_b32_e32 v1, v197
	v_readlane_b32 s0, v253, 6
	v_ashrrev_i32_e32 v3, 6, v1
	s_nop 0
	v_add_u32_e32 v4, s0, v3
	s_mov_b32 s0, 0x9000
	v_cmp_gt_i32_e32 vcc, s0, v4
	s_and_saveexec_b64 s[4:5], vcc
	s_cbranch_execz .LBB0_261
	s_waitcnt vmcnt(0) lgkmcnt(0)
	v_readlane_b32 s6, v254, 41
	v_readlane_b32 s7, v254, 42
	v_readfirstlane_b32 s18, v4
	v_readlane_b32 s23, v254, 53
	v_readlane_b32 s3, v253, 7
	s_load_dwordx2 s[0:1], s[6:7], 0x30
	s_load_dwordx4 s[8:11], s[6:7], 0x118
	v_and_b32_e32 v7, 63, v197
	v_lshlrev_b32_e32 v6, 4, v7
	v_lshlrev_b32_e32 v7, 3, v7
	s_lshl_b32 s40, s23, 12
	s_mul_i32 s41, s23, 0x66000
	s_add_u32 s41, s41, 0x1000
	s_waitcnt lgkmcnt(0)
	s_add_u32 s0, s0, s40
	s_addc_u32 s1, s1, 0
	s_add_u32 s12, s10, 0x198100
	s_addc_u32 s13, s11, 0
	s_add_u32 s14, s10, s41
	s_addc_u32 s15, s11, 0
	s_add_u32 s20, s10, 0x3998100
	s_addc_u32 s21, s11, 0
	s_mov_b32 s50, 1
	s_cmp_lg_u32 s23, 0
	s_cbranch_scc1 .Lnm0_norm
	s_load_dwordx2 s[64:65], s[6:7], 0x0
	s_load_dwordx2 s[66:67], s[6:7], 0x10
	s_waitcnt lgkmcnt(0)
	s_mul_hi_u32 s40, s18, 0x71c72
	s_mul_i32 s41, s40, 0x2400
	s_sub_u32 s41, s18, s41
	s_lshr_b32 s42, s41, 11
	s_lshl2_add_u32 s42, s40, s42
	s_sub_u32 s43, s41, 0x2000
	s_cmp_lt_u32 s41, 0x2000
	s_cselect_b32 s42, s42, 16
	s_cselect_b32 s43, s41, s43
	s_cselect_b32 s44, 25, 22
	s_cselect_b32 s48, s8, s12
	s_cselect_b32 s49, s9, s13
	s_cselect_b32 s72, s64, s66
	s_cselect_b32 s73, s65, s67
	s_lshl_b32 s44, s40, s44
	s_lshl_b32 s43, s43, 12
	s_add_u32 s43, s43, s44
	s_add_u32 s24, s48, s43
	s_addc_u32 s25, s49, 0
	s_add_u32 s74, s72, s43
	s_addc_u32 s75, s73, 0
	s_mul_i32 s42, s42, 0x6000
	s_add_u32 s26, s14, s42
	s_addc_u32 s27, s15, 0
	s_lshl_b32 s43, s18, 11
	s_add_u32 s28, s20, s43
	s_addc_u32 s29, s21, 0
	global_load_dwordx4 v[8:11], v6, s[74:75]
	global_load_dwordx4 v[12:15], v6, s[74:75] offset:1024
	global_load_dwordx4 v[16:19], v6, s[74:75] offset:2048
	global_load_dwordx4 v[20:23], v6, s[74:75] offset:3072
	global_load_dwordx4 v[24:27], v6, s[26:27]
	global_load_dwordx4 v[28:31], v6, s[26:27] offset:1024
	global_load_dwordx4 v[32:35], v6, s[26:27] offset:2048
	global_load_dwordx4 v[36:39], v6, s[26:27] offset:3072
	global_load_dwordx4 v[40:43], v6, s[26:27] offset:-4096
	global_load_dwordx4 v[44:47], v6, s[26:27] offset:-3072
	global_load_dwordx4 v[48:51], v6, s[26:27] offset:-2048
	global_load_dwordx4 v[52:55], v6, s[26:27] offset:-1024
	global_load_dwordx4 v[88:91], v6, s[0:1]
	global_load_dwordx4 v[92:95], v6, s[0:1] offset:1024
	global_load_dwordx4 v[96:99], v6, s[0:1] offset:2048
	global_load_dwordx4 v[100:103], v6, s[0:1] offset:3072
.Lnm0c_loop:
	s_add_u32 s23, s18, s3
	s_cmp_lt_u32 s23, 0x9000
	s_cbranch_scc0 .Lnm0c_lastA
	s_mul_hi_u32 s40, s23, 0x71c72
	s_mul_i32 s41, s40, 0x2400
	s_sub_u32 s41, s23, s41
	s_lshr_b32 s42, s41, 11
	s_lshl2_add_u32 s42, s40, s42
	s_sub_u32 s43, s41, 0x2000
	s_cmp_lt_u32 s41, 0x2000
	s_cselect_b32 s42, s42, 16
	s_cselect_b32 s43, s41, s43
	s_cselect_b32 s44, 25, 22
	s_cselect_b32 s48, s8, s12
	s_cselect_b32 s49, s9, s13
	s_cselect_b32 s72, s64, s66
	s_cselect_b32 s73, s65, s67
	s_lshl_b32 s44, s40, s44
	s_lshl_b32 s43, s43, 12
	s_add_u32 s43, s43, s44
	s_add_u32 s30, s48, s43
	s_addc_u32 s31, s49, 0
	s_add_u32 s76, s72, s43
	s_addc_u32 s77, s73, 0
	s_mul_i32 s42, s42, 0x6000
	s_add_u32 s36, s14, s42
	s_addc_u32 s37, s15, 0
	s_lshl_b32 s43, s23, 11
	s_add_u32 s38, s20, s43
	s_addc_u32 s39, s21, 0
	global_load_dwordx4 v[104:107], v6, s[76:77]
	global_load_dwordx4 v[108:111], v6, s[76:77] offset:1024
	global_load_dwordx4 v[112:115], v6, s[76:77] offset:2048
	global_load_dwordx4 v[116:119], v6, s[76:77] offset:3072
	global_load_dwordx4 v[120:123], v6, s[36:37]
	global_load_dwordx4 v[124:127], v6, s[36:37] offset:1024
	global_load_dwordx4 v[128:131], v6, s[36:37] offset:2048
	global_load_dwordx4 v[132:135], v6, s[36:37] offset:3072
	global_load_dwordx4 v[164:167], v6, s[36:37] offset:-4096
	global_load_dwordx4 v[168:171], v6, s[36:37] offset:-3072
	global_load_dwordx4 v[172:175], v6, s[36:37] offset:-2048
	global_load_dwordx4 v[176:179], v6, s[36:37] offset:-1024
	s_waitcnt vmcnt(20)
	global_store_dwordx4 v6, v[8:11], s[24:25]
	global_store_dwordx4 v6, v[12:15], s[24:25] offset:1024
	global_store_dwordx4 v6, v[16:19], s[24:25] offset:2048
	global_store_dwordx4 v6, v[20:23], s[24:25] offset:3072
	v_pk_mul_f32 v[56:57], v[8:9], v[8:9]
	v_pk_mul_f32 v[58:59], v[10:11], v[10:11]
	v_pk_fma_f32 v[56:57], v[12:13], v[12:13], v[56:57]
	v_pk_fma_f32 v[58:59], v[14:15], v[14:15], v[58:59]
	v_pk_fma_f32 v[56:57], v[16:17], v[16:17], v[56:57]
	v_pk_fma_f32 v[58:59], v[18:19], v[18:19], v[58:59]
	v_pk_fma_f32 v[56:57], v[20:21], v[20:21], v[56:57]
	v_pk_fma_f32 v[58:59], v[22:23], v[22:23], v[58:59]
	v_pk_add_f32 v[56:57], v[56:57], v[58:59]
	v_pk_add_f32 v[24:25], v[24:25], 1.0 op_sel_hi:[1,0]
	v_add_f32_e32 v60, v56, v57
	v_pk_add_f32 v[26:27], v[26:27], 1.0 op_sel_hi:[1,0]
	v_pk_add_f32 v[28:29], v[28:29], 1.0 op_sel_hi:[1,0]
	v_add_f32_dpp v60, v60, v60 quad_perm:[1,0,3,2] row_mask:0xf bank_mask:0xf
	v_pk_add_f32 v[30:31], v[30:31], 1.0 op_sel_hi:[1,0]
	v_pk_add_f32 v[32:33], v[32:33], 1.0 op_sel_hi:[1,0]
	v_add_f32_dpp v60, v60, v60 quad_perm:[2,3,0,1] row_mask:0xf bank_mask:0xf
	v_pk_add_f32 v[34:35], v[34:35], 1.0 op_sel_hi:[1,0]
	v_pk_add_f32 v[36:37], v[36:37], 1.0 op_sel_hi:[1,0]
	v_add_f32_dpp v60, v60, v60 row_half_mirror row_mask:0xf bank_mask:0xf
	v_pk_add_f32 v[38:39], v[38:39], 1.0 op_sel_hi:[1,0]
	s_nop 0
	v_add_f32_dpp v60, v60, v60 row_mirror row_mask:0xf bank_mask:0xf
	s_nop 1
	v_readlane_b32 s60, v60, 0
	v_readlane_b32 s61, v60, 16
	v_readlane_b32 s62, v60, 32
	v_readlane_b32 s63, v60, 48
	v_mov_b32_e32 v60, s60
	s_nop 0
	v_add_f32_e32 v60, s61, v60
	v_add_f32_e32 v60, s62, v60
	v_add_f32_e32 v60, s63, v60
	v_fmamk_f32 v60, v60, 0x3a800000, v233
	v_rsq_f32_e32 v62, v60
	s_cmp_eq_u32 s50, 0
	s_cbranch_scc1 .Lnm0c_g1
	s_waitcnt vmcnt(12)
	s_mov_b32 s50, 0
.Lnm0c_g1:
	v_pk_mul_f32 v[8:9], v[8:9], v[62:63] op_sel_hi:[1,0]
	v_pk_mul_f32 v[10:11], v[10:11], v[62:63] op_sel_hi:[1,0]
	v_pk_mul_f32 v[12:13], v[12:13], v[62:63] op_sel_hi:[1,0]
	v_pk_mul_f32 v[14:15], v[14:15], v[62:63] op_sel_hi:[1,0]
	v_pk_mul_f32 v[16:17], v[16:17], v[62:63] op_sel_hi:[1,0]
	v_pk_mul_f32 v[18:19], v[18:19], v[62:63] op_sel_hi:[1,0]
	v_pk_mul_f32 v[20:21], v[20:21], v[62:63] op_sel_hi:[1,0]
	v_pk_mul_f32 v[22:23], v[22:23], v[62:63] op_sel_hi:[1,0]
	v_pk_mul_f32 v[8:9], v[88:89], v[8:9]
	v_pk_mul_f32 v[10:11], v[90:91], v[10:11]
	v_pk_mul_f32 v[12:13], v[92:93], v[12:13]
	v_pk_mul_f32 v[14:15], v[94:95], v[14:15]
	v_pk_mul_f32 v[16:17], v[96:97], v[16:17]
	v_pk_mul_f32 v[18:19], v[98:99], v[18:19]
	v_pk_mul_f32 v[20:21], v[100:101], v[20:21]
	v_pk_mul_f32 v[22:23], v[102:103], v[22:23]
	v_pk_fma_f32 v[8:9], v[24:25], v[8:9], v[40:41]
	v_pk_fma_f32 v[10:11], v[26:27], v[10:11], v[42:43]
	v_pk_fma_f32 v[12:13], v[28:29], v[12:13], v[44:45]
	v_pk_fma_f32 v[14:15], v[30:31], v[14:15], v[46:47]
	v_pk_fma_f32 v[16:17], v[32:33], v[16:17], v[48:49]
	v_pk_fma_f32 v[18:19], v[34:35], v[18:19], v[50:51]
	v_pk_fma_f32 v[20:21], v[36:37], v[20:21], v[52:53]
	v_pk_fma_f32 v[22:23], v[38:39], v[22:23], v[54:55]
	v_cvt_pk_f16_f32 v8, v8, v9
	v_cvt_pk_f16_f32 v9, v10, v11
	v_cvt_pk_f16_f32 v10, v12, v13
	v_cvt_pk_f16_f32 v11, v14, v15
	v_cvt_pk_f16_f32 v12, v16, v17
	v_cvt_pk_f16_f32 v13, v18, v19
	v_cvt_pk_f16_f32 v14, v20, v21
	v_cvt_pk_f16_f32 v15, v22, v23
	global_store_dwordx2 v7, v[8:9], s[28:29]
	global_store_dwordx2 v7, v[10:11], s[28:29] offset:512
	global_store_dwordx2 v7, v[12:13], s[28:29] offset:1024
	global_store_dwordx2 v7, v[14:15], s[28:29] offset:1536
	s_add_u32 s18, s23, s3
	s_cmp_lt_u32 s18, 0x9000
	s_cbranch_scc0 .Lnm0c_lastB
	s_mul_hi_u32 s40, s18, 0x71c72
	s_mul_i32 s41, s40, 0x2400
	s_sub_u32 s41, s18, s41
	s_lshr_b32 s42, s41, 11
	s_lshl2_add_u32 s42, s40, s42
	s_sub_u32 s43, s41, 0x2000
	s_cmp_lt_u32 s41, 0x2000
	s_cselect_b32 s42, s42, 16
	s_cselect_b32 s43, s41, s43
	s_cselect_b32 s44, 25, 22
	s_cselect_b32 s48, s8, s12
	s_cselect_b32 s49, s9, s13
	s_cselect_b32 s72, s64, s66
	s_cselect_b32 s73, s65, s67
	s_lshl_b32 s44, s40, s44
	s_lshl_b32 s43, s43, 12
	s_add_u32 s43, s43, s44
	s_add_u32 s24, s48, s43
	s_addc_u32 s25, s49, 0
	s_add_u32 s74, s72, s43
	s_addc_u32 s75, s73, 0
	s_mul_i32 s42, s42, 0x6000
	s_add_u32 s26, s14, s42
	s_addc_u32 s27, s15, 0
	s_lshl_b32 s43, s18, 11
	s_add_u32 s28, s20, s43
	s_addc_u32 s29, s21, 0
	global_load_dwordx4 v[8:11], v6, s[74:75]
	global_load_dwordx4 v[12:15], v6, s[74:75] offset:1024
	global_load_dwordx4 v[16:19], v6, s[74:75] offset:2048
	global_load_dwordx4 v[20:23], v6, s[74:75] offset:3072
	global_load_dwordx4 v[24:27], v6, s[26:27]
	global_load_dwordx4 v[28:31], v6, s[26:27] offset:1024
	global_load_dwordx4 v[32:35], v6, s[26:27] offset:2048
	global_load_dwordx4 v[36:39], v6, s[26:27] offset:3072
	global_load_dwordx4 v[40:43], v6, s[26:27] offset:-4096
	global_load_dwordx4 v[44:47], v6, s[26:27] offset:-3072
	global_load_dwordx4 v[48:51], v6, s[26:27] offset:-2048
	global_load_dwordx4 v[52:55], v6, s[26:27] offset:-1024
	s_waitcnt vmcnt(20)
	global_store_dwordx4 v6, v[104:107], s[30:31]
	global_store_dwordx4 v6, v[108:111], s[30:31] offset:1024
	global_store_dwordx4 v6, v[112:115], s[30:31] offset:2048
	global_store_dwordx4 v6, v[116:119], s[30:31] offset:3072
	v_pk_mul_f32 v[56:57], v[104:105], v[104:105]
	v_pk_mul_f32 v[58:59], v[106:107], v[106:107]
	v_pk_fma_f32 v[56:57], v[108:109], v[108:109], v[56:57]
	v_pk_fma_f32 v[58:59], v[110:111], v[110:111], v[58:59]
	v_pk_fma_f32 v[56:57], v[112:113], v[112:113], v[56:57]
	v_pk_fma_f32 v[58:59], v[114:115], v[114:115], v[58:59]
	v_pk_fma_f32 v[56:57], v[116:117], v[116:117], v[56:57]
	v_pk_fma_f32 v[58:59], v[118:119], v[118:119], v[58:59]
	v_pk_add_f32 v[56:57], v[56:57], v[58:59]
	v_pk_add_f32 v[120:121], v[120:121], 1.0 op_sel_hi:[1,0]
	v_add_f32_e32 v60, v56, v57
	v_pk_add_f32 v[122:123], v[122:123], 1.0 op_sel_hi:[1,0]
	v_pk_add_f32 v[124:125], v[124:125], 1.0 op_sel_hi:[1,0]
	v_add_f32_dpp v60, v60, v60 quad_perm:[1,0,3,2] row_mask:0xf bank_mask:0xf
	v_pk_add_f32 v[126:127], v[126:127], 1.0 op_sel_hi:[1,0]
	v_pk_add_f32 v[128:129], v[128:129], 1.0 op_sel_hi:[1,0]
	v_add_f32_dpp v60, v60, v60 quad_perm:[2,3,0,1] row_mask:0xf bank_mask:0xf
	v_pk_add_f32 v[130:131], v[130:131], 1.0 op_sel_hi:[1,0]
	v_pk_add_f32 v[132:133], v[132:133], 1.0 op_sel_hi:[1,0]
	v_add_f32_dpp v60, v60, v60 row_half_mirror row_mask:0xf bank_mask:0xf
	v_pk_add_f32 v[134:135], v[134:135], 1.0 op_sel_hi:[1,0]
	s_nop 0
	v_add_f32_dpp v60, v60, v60 row_mirror row_mask:0xf bank_mask:0xf
	s_nop 1
	v_readlane_b32 s60, v60, 0
	v_readlane_b32 s61, v60, 16
	v_readlane_b32 s62, v60, 32
	v_readlane_b32 s63, v60, 48
	v_mov_b32_e32 v60, s60
	s_nop 0
	v_add_f32_e32 v60, s61, v60
	v_add_f32_e32 v60, s62, v60
	v_add_f32_e32 v60, s63, v60
	v_fmamk_f32 v60, v60, 0x3a800000, v233
	v_rsq_f32_e32 v62, v60
	s_nop 0
	v_pk_mul_f32 v[104:105], v[104:105], v[62:63] op_sel_hi:[1,0]
	v_pk_mul_f32 v[106:107], v[106:107], v[62:63] op_sel_hi:[1,0]
	v_pk_mul_f32 v[108:109], v[108:109], v[62:63] op_sel_hi:[1,0]
	v_pk_mul_f32 v[110:111], v[110:111], v[62:63] op_sel_hi:[1,0]
	v_pk_mul_f32 v[112:113], v[112:113], v[62:63] op_sel_hi:[1,0]
	v_pk_mul_f32 v[114:115], v[114:115], v[62:63] op_sel_hi:[1,0]
	v_pk_mul_f32 v[116:117], v[116:117], v[62:63] op_sel_hi:[1,0]
	v_pk_mul_f32 v[118:119], v[118:119], v[62:63] op_sel_hi:[1,0]
	v_pk_mul_f32 v[104:105], v[88:89], v[104:105]
	v_pk_mul_f32 v[106:107], v[90:91], v[106:107]
	v_pk_mul_f32 v[108:109], v[92:93], v[108:109]
	v_pk_mul_f32 v[110:111], v[94:95], v[110:111]
	v_pk_mul_f32 v[112:113], v[96:97], v[112:113]
	v_pk_mul_f32 v[114:115], v[98:99], v[114:115]
	v_pk_mul_f32 v[116:117], v[100:101], v[116:117]
	v_pk_mul_f32 v[118:119], v[102:103], v[118:119]
	v_pk_fma_f32 v[104:105], v[120:121], v[104:105], v[164:165]
	v_pk_fma_f32 v[106:107], v[122:123], v[106:107], v[166:167]
	v_pk_fma_f32 v[108:109], v[124:125], v[108:109], v[168:169]
	v_pk_fma_f32 v[110:111], v[126:127], v[110:111], v[170:171]
	v_pk_fma_f32 v[112:113], v[128:129], v[112:113], v[172:173]
	v_pk_fma_f32 v[114:115], v[130:131], v[114:115], v[174:175]
	v_pk_fma_f32 v[116:117], v[132:133], v[116:117], v[176:177]
	v_pk_fma_f32 v[118:119], v[134:135], v[118:119], v[178:179]
	v_cvt_pk_f16_f32 v104, v104, v105
	v_cvt_pk_f16_f32 v105, v106, v107
	v_cvt_pk_f16_f32 v106, v108, v109
	v_cvt_pk_f16_f32 v107, v110, v111
	v_cvt_pk_f16_f32 v108, v112, v113
	v_cvt_pk_f16_f32 v109, v114, v115
	v_cvt_pk_f16_f32 v110, v116, v117
	v_cvt_pk_f16_f32 v111, v118, v119
	global_store_dwordx2 v7, v[104:105], s[38:39]
	global_store_dwordx2 v7, v[106:107], s[38:39] offset:512
	global_store_dwordx2 v7, v[108:109], s[38:39] offset:1024
	global_store_dwordx2 v7, v[110:111], s[38:39] offset:1536
	s_branch .Lnm0c_loop
.Lnm0c_lastA:
	s_waitcnt vmcnt(0)
	global_store_dwordx4 v6, v[8:11], s[24:25]
	global_store_dwordx4 v6, v[12:15], s[24:25] offset:1024
	global_store_dwordx4 v6, v[16:19], s[24:25] offset:2048
	global_store_dwordx4 v6, v[20:23], s[24:25] offset:3072
	v_pk_mul_f32 v[56:57], v[8:9], v[8:9]
	v_pk_mul_f32 v[58:59], v[10:11], v[10:11]
	v_pk_fma_f32 v[56:57], v[12:13], v[12:13], v[56:57]
	v_pk_fma_f32 v[58:59], v[14:15], v[14:15], v[58:59]
	v_pk_fma_f32 v[56:57], v[16:17], v[16:17], v[56:57]
	v_pk_fma_f32 v[58:59], v[18:19], v[18:19], v[58:59]
	v_pk_fma_f32 v[56:57], v[20:21], v[20:21], v[56:57]
	v_pk_fma_f32 v[58:59], v[22:23], v[22:23], v[58:59]
	v_pk_add_f32 v[56:57], v[56:57], v[58:59]
	v_pk_add_f32 v[24:25], v[24:25], 1.0 op_sel_hi:[1,0]
	v_add_f32_e32 v60, v56, v57
	v_pk_add_f32 v[26:27], v[26:27], 1.0 op_sel_hi:[1,0]
	v_pk_add_f32 v[28:29], v[28:29], 1.0 op_sel_hi:[1,0]
	v_add_f32_dpp v60, v60, v60 quad_perm:[1,0,3,2] row_mask:0xf bank_mask:0xf
	v_pk_add_f32 v[30:31], v[30:31], 1.0 op_sel_hi:[1,0]
	v_pk_add_f32 v[32:33], v[32:33], 1.0 op_sel_hi:[1,0]
	v_add_f32_dpp v60, v60, v60 quad_perm:[2,3,0,1] row_mask:0xf bank_mask:0xf
	v_pk_add_f32 v[34:35], v[34:35], 1.0 op_sel_hi:[1,0]
	v_pk_add_f32 v[36:37], v[36:37], 1.0 op_sel_hi:[1,0]
	v_add_f32_dpp v60, v60, v60 row_half_mirror row_mask:0xf bank_mask:0xf
	v_pk_add_f32 v[38:39], v[38:39], 1.0 op_sel_hi:[1,0]
	s_nop 0
	v_add_f32_dpp v60, v60, v60 row_mirror row_mask:0xf bank_mask:0xf
	s_nop 1
	v_readlane_b32 s60, v60, 0
	v_readlane_b32 s61, v60, 16
	v_readlane_b32 s62, v60, 32
	v_readlane_b32 s63, v60, 48
	v_mov_b32_e32 v60, s60
	s_nop 0
	v_add_f32_e32 v60, s61, v60
	v_add_f32_e32 v60, s62, v60
	v_add_f32_e32 v60, s63, v60
	v_fmamk_f32 v60, v60, 0x3a800000, v233
	v_rsq_f32_e32 v62, v60
	s_nop 0
	v_pk_mul_f32 v[8:9], v[8:9], v[62:63] op_sel_hi:[1,0]
	v_pk_mul_f32 v[10:11], v[10:11], v[62:63] op_sel_hi:[1,0]
	v_pk_mul_f32 v[12:13], v[12:13], v[62:63] op_sel_hi:[1,0]
	v_pk_mul_f32 v[14:15], v[14:15], v[62:63] op_sel_hi:[1,0]
	v_pk_mul_f32 v[16:17], v[16:17], v[62:63] op_sel_hi:[1,0]
	v_pk_mul_f32 v[18:19], v[18:19], v[62:63] op_sel_hi:[1,0]
	v_pk_mul_f32 v[20:21], v[20:21], v[62:63] op_sel_hi:[1,0]
	v_pk_mul_f32 v[22:23], v[22:23], v[62:63] op_sel_hi:[1,0]
	v_pk_mul_f32 v[8:9], v[88:89], v[8:9]
	v_pk_mul_f32 v[10:11], v[90:91], v[10:11]
	v_pk_mul_f32 v[12:13], v[92:93], v[12:13]
	v_pk_mul_f32 v[14:15], v[94:95], v[14:15]
	v_pk_mul_f32 v[16:17], v[96:97], v[16:17]
	v_pk_mul_f32 v[18:19], v[98:99], v[18:19]
	v_pk_mul_f32 v[20:21], v[100:101], v[20:21]
	v_pk_mul_f32 v[22:23], v[102:103], v[22:23]
	v_pk_fma_f32 v[8:9], v[24:25], v[8:9], v[40:41]
	v_pk_fma_f32 v[10:11], v[26:27], v[10:11], v[42:43]
	v_pk_fma_f32 v[12:13], v[28:29], v[12:13], v[44:45]
	v_pk_fma_f32 v[14:15], v[30:31], v[14:15], v[46:47]
	v_pk_fma_f32 v[16:17], v[32:33], v[16:17], v[48:49]
	v_pk_fma_f32 v[18:19], v[34:35], v[18:19], v[50:51]
	v_pk_fma_f32 v[20:21], v[36:37], v[20:21], v[52:53]
	v_pk_fma_f32 v[22:23], v[38:39], v[22:23], v[54:55]
	v_cvt_pk_f16_f32 v8, v8, v9
	v_cvt_pk_f16_f32 v9, v10, v11
	v_cvt_pk_f16_f32 v10, v12, v13
	v_cvt_pk_f16_f32 v11, v14, v15
	v_cvt_pk_f16_f32 v12, v16, v17
	v_cvt_pk_f16_f32 v13, v18, v19
	v_cvt_pk_f16_f32 v14, v20, v21
	v_cvt_pk_f16_f32 v15, v22, v23
	global_store_dwordx2 v7, v[8:9], s[28:29]
	global_store_dwordx2 v7, v[10:11], s[28:29] offset:512
	global_store_dwordx2 v7, v[12:13], s[28:29] offset:1024
	global_store_dwordx2 v7, v[14:15], s[28:29] offset:1536
	s_branch .Lnm0c_end
.Lnm0c_lastB:
	s_waitcnt vmcnt(0)
	global_store_dwordx4 v6, v[104:107], s[30:31]
	global_store_dwordx4 v6, v[108:111], s[30:31] offset:1024
	global_store_dwordx4 v6, v[112:115], s[30:31] offset:2048
	global_store_dwordx4 v6, v[116:119], s[30:31] offset:3072
	v_pk_mul_f32 v[56:57], v[104:105], v[104:105]
	v_pk_mul_f32 v[58:59], v[106:107], v[106:107]
	v_pk_fma_f32 v[56:57], v[108:109], v[108:109], v[56:57]
	v_pk_fma_f32 v[58:59], v[110:111], v[110:111], v[58:59]
	v_pk_fma_f32 v[56:57], v[112:113], v[112:113], v[56:57]
	v_pk_fma_f32 v[58:59], v[114:115], v[114:115], v[58:59]
	v_pk_fma_f32 v[56:57], v[116:117], v[116:117], v[56:57]
	v_pk_fma_f32 v[58:59], v[118:119], v[118:119], v[58:59]
	v_pk_add_f32 v[56:57], v[56:57], v[58:59]
	v_pk_add_f32 v[120:121], v[120:121], 1.0 op_sel_hi:[1,0]
	v_add_f32_e32 v60, v56, v57
	v_pk_add_f32 v[122:123], v[122:123], 1.0 op_sel_hi:[1,0]
	v_pk_add_f32 v[124:125], v[124:125], 1.0 op_sel_hi:[1,0]
	v_add_f32_dpp v60, v60, v60 quad_perm:[1,0,3,2] row_mask:0xf bank_mask:0xf
	v_pk_add_f32 v[126:127], v[126:127], 1.0 op_sel_hi:[1,0]
	v_pk_add_f32 v[128:129], v[128:129], 1.0 op_sel_hi:[1,0]
	v_add_f32_dpp v60, v60, v60 quad_perm:[2,3,0,1] row_mask:0xf bank_mask:0xf
	v_pk_add_f32 v[130:131], v[130:131], 1.0 op_sel_hi:[1,0]
	v_pk_add_f32 v[132:133], v[132:133], 1.0 op_sel_hi:[1,0]
	v_add_f32_dpp v60, v60, v60 row_half_mirror row_mask:0xf bank_mask:0xf
	v_pk_add_f32 v[134:135], v[134:135], 1.0 op_sel_hi:[1,0]
	s_nop 0
	v_add_f32_dpp v60, v60, v60 row_mirror row_mask:0xf bank_mask:0xf
	s_nop 1
	v_readlane_b32 s60, v60, 0
	v_readlane_b32 s61, v60, 16
	v_readlane_b32 s62, v60, 32
	v_readlane_b32 s63, v60, 48
	v_mov_b32_e32 v60, s60
	s_nop 0
	v_add_f32_e32 v60, s61, v60
	v_add_f32_e32 v60, s62, v60
	v_add_f32_e32 v60, s63, v60
	v_fmamk_f32 v60, v60, 0x3a800000, v233
	v_rsq_f32_e32 v62, v60
	s_nop 0
	v_pk_mul_f32 v[104:105], v[104:105], v[62:63] op_sel_hi:[1,0]
	v_pk_mul_f32 v[106:107], v[106:107], v[62:63] op_sel_hi:[1,0]
	v_pk_mul_f32 v[108:109], v[108:109], v[62:63] op_sel_hi:[1,0]
	v_pk_mul_f32 v[110:111], v[110:111], v[62:63] op_sel_hi:[1,0]
	v_pk_mul_f32 v[112:113], v[112:113], v[62:63] op_sel_hi:[1,0]
	v_pk_mul_f32 v[114:115], v[114:115], v[62:63] op_sel_hi:[1,0]
	v_pk_mul_f32 v[116:117], v[116:117], v[62:63] op_sel_hi:[1,0]
	v_pk_mul_f32 v[118:119], v[118:119], v[62:63] op_sel_hi:[1,0]
	v_pk_mul_f32 v[104:105], v[88:89], v[104:105]
	v_pk_mul_f32 v[106:107], v[90:91], v[106:107]
	v_pk_mul_f32 v[108:109], v[92:93], v[108:109]
	v_pk_mul_f32 v[110:111], v[94:95], v[110:111]
	v_pk_mul_f32 v[112:113], v[96:97], v[112:113]
	v_pk_mul_f32 v[114:115], v[98:99], v[114:115]
	v_pk_mul_f32 v[116:117], v[100:101], v[116:117]
	v_pk_mul_f32 v[118:119], v[102:103], v[118:119]
	v_pk_fma_f32 v[104:105], v[120:121], v[104:105], v[164:165]
	v_pk_fma_f32 v[106:107], v[122:123], v[106:107], v[166:167]
	v_pk_fma_f32 v[108:109], v[124:125], v[108:109], v[168:169]
	v_pk_fma_f32 v[110:111], v[126:127], v[110:111], v[170:171]
	v_pk_fma_f32 v[112:113], v[128:129], v[112:113], v[172:173]
	v_pk_fma_f32 v[114:115], v[130:131], v[114:115], v[174:175]
	v_pk_fma_f32 v[116:117], v[132:133], v[116:117], v[176:177]
	v_pk_fma_f32 v[118:119], v[134:135], v[118:119], v[178:179]
	v_cvt_pk_f16_f32 v104, v104, v105
	v_cvt_pk_f16_f32 v105, v106, v107
	v_cvt_pk_f16_f32 v106, v108, v109
	v_cvt_pk_f16_f32 v107, v110, v111
	v_cvt_pk_f16_f32 v108, v112, v113
	v_cvt_pk_f16_f32 v109, v114, v115
	v_cvt_pk_f16_f32 v110, v116, v117
	v_cvt_pk_f16_f32 v111, v118, v119
	global_store_dwordx2 v7, v[104:105], s[38:39]
	global_store_dwordx2 v7, v[106:107], s[38:39] offset:512
	global_store_dwordx2 v7, v[108:109], s[38:39] offset:1024
	global_store_dwordx2 v7, v[110:111], s[38:39] offset:1536
.Lnm0c_end:
	s_branch .Lnm0_done
.Lnm0_norm:
	s_mul_hi_u32 s40, s18, 0x71c72
	s_mul_i32 s41, s40, 0x2400
	s_sub_u32 s41, s18, s41
	s_lshr_b32 s42, s41, 11
	s_lshl2_add_u32 s42, s40, s42
	s_sub_u32 s43, s41, 0x2000
	s_cmp_lt_u32 s41, 0x2000
	s_cselect_b32 s42, s42, 16
	s_cselect_b32 s43, s41, s43
	s_cselect_b32 s44, 25, 22
	s_cselect_b32 s48, s8, s12
	s_cselect_b32 s49, s9, s13
	s_lshl_b32 s44, s40, s44
	s_lshl_b32 s43, s43, 12
	s_add_u32 s43, s43, s44
	s_add_u32 s24, s48, s43
	s_addc_u32 s25, s49, 0
	s_mul_i32 s42, s42, 0x6000
	s_add_u32 s26, s14, s42
	s_addc_u32 s27, s15, 0
	s_lshl_b32 s43, s18, 11
	s_add_u32 s28, s20, s43
	s_addc_u32 s29, s21, 0
	global_load_dwordx4 v[8:11], v6, s[24:25]
	global_load_dwordx4 v[12:15], v6, s[24:25] offset:1024
	global_load_dwordx4 v[16:19], v6, s[24:25] offset:2048
	global_load_dwordx4 v[20:23], v6, s[24:25] offset:3072
	global_load_dwordx4 v[24:27], v6, s[26:27]
	global_load_dwordx4 v[28:31], v6, s[26:27] offset:1024
	global_load_dwordx4 v[32:35], v6, s[26:27] offset:2048
	global_load_dwordx4 v[36:39], v6, s[26:27] offset:3072
	global_load_dwordx4 v[40:43], v6, s[26:27] offset:-4096
	global_load_dwordx4 v[44:47], v6, s[26:27] offset:-3072
	global_load_dwordx4 v[48:51], v6, s[26:27] offset:-2048
	global_load_dwordx4 v[52:55], v6, s[26:27] offset:-1024
	global_load_dwordx4 v[88:91], v6, s[0:1]
	global_load_dwordx4 v[92:95], v6, s[0:1] offset:1024
	global_load_dwordx4 v[96:99], v6, s[0:1] offset:2048
	global_load_dwordx4 v[100:103], v6, s[0:1] offset:3072

.LBB0_269:
	s_andn2_b64 vcc, exec, s[4:5]
	s_cbranch_vccnz .LBB0_297
	s_cmp_gt_i32 s33, 0
	s_mov_b64 s[4:5], -1
	s_cbranch_scc0 .LBB0_286
	s_mov_b64 s[4:5], 0
	s_branch .LBB0_286
	v_readlane_b32 s0, v254, 41
	v_readlane_b32 s1, v254, 42
	s_waitcnt lgkmcnt(0)
	s_load_dwordx2 s[12:13], s[0:1], 0x0
	s_load_dwordx2 s[4:5], s[0:1], 0x10
	s_load_dwordx4 s[8:11], s[0:1], 0x118
	s_waitcnt vmcnt(0)
	v_mov_b32_e32 v10, v197
	v_readlane_b32 s0, v253, 12
	v_readlane_b32 s1, v253, 13
	v_ashrrev_i32_e32 v11, 31, v10
	s_nop 0
	v_lshl_add_u64 v[4:5], s[0:1], 0, v[10:11]
	v_readlane_b32 s0, v253, 21
	v_readlane_b32 s1, v253, 22
	s_nop 1
	v_lshl_add_u64 v[6:7], v[4:5], 0, s[0:1]
	s_mov_b64 s[0:1], 0x800000
	v_cmp_gt_u64_e32 vcc, s[0:1], v[6:7]
	s_and_saveexec_b64 s[14:15], vcc
	s_cbranch_execz .LBB0_275
	v_readlane_b32 s3, v253, 30
	s_waitcnt lgkmcnt(0)
	s_add_u32 s0, s8, s3
	v_readlane_b32 s16, v253, 32
	s_addc_u32 s1, s9, s16
	v_lshlrev_b64 v[20:21], 4, v[10:11]
	v_readlane_b32 s17, v253, 34
	v_lshl_add_u64 v[10:11], s[0:1], 0, v[20:21]
	s_add_u32 s0, s8, s17
	v_readlane_b32 s18, v253, 36
	s_addc_u32 s1, s9, s18
	v_readlane_b32 s6, v253, 28
	v_lshl_add_u64 v[12:13], s[0:1], 0, v[20:21]
	v_readlane_b32 s7, v253, 29
	s_add_u32 s0, s8, s6
	s_addc_u32 s1, s9, s7
	v_lshl_add_u64 v[14:15], s[0:1], 0, v[20:21]
	s_add_u32 s0, s12, s3
	s_addc_u32 s1, s13, s16
	v_lshl_add_u64 v[16:17], s[0:1], 0, v[20:21]
	s_add_u32 s0, s12, s17
	s_addc_u32 s1, s13, s18
	v_lshl_add_u64 v[18:19], s[0:1], 0, v[20:21]
	s_add_u32 s0, s12, s6
	s_addc_u32 s1, s13, s7
	v_lshlrev_b64 v[8:9], 4, v[6:7]
	v_lshl_add_u64 v[20:21], s[0:1], 0, v[20:21]
	v_readlane_b32 s0, v253, 21
	v_readlane_b32 s6, v254, 37
	v_readlane_b32 s20, v253, 26
	v_lshl_add_u64 v[6:7], s[8:9], 0, v[8:9]
	v_lshl_add_u64 v[8:9], s[12:13], 0, v[8:9]
	s_mov_b64 s[16:17], 0
	s_mov_b64 s[18:19], 0
	v_readlane_b32 s1, v253, 22
	v_readlane_b32 s7, v254, 38
	v_readlane_b32 s21, v253, 27
	s_mov_b64 s[22:23], 0x7fffff
